# hand-scheduled RWKV scan chunk body: burst LDS prefetch one pair ahead, grouped counted lgkmcnt waits, no register copies; attention V staging conflict-free
# speedup vs baseline: 1.0196x; 1.0147x over previous
.LBB0_496:
	s_and_b32 s54, s58, 1
	s_waitcnt lgkmcnt(0)
	s_barrier
	s_and_saveexec_b64 s[40:41], s[4:5]
	s_xor_b64 s[52:53], exec, s[40:41]
	s_cbranch_execz .LBB0_498
	s_mov_b32 s11, s10
	s_mov_b32 s15, s14
	s_mov_b32 s35, s34
	s_mov_b32 s37, s36
	s_mov_b32 s43, s42
	s_mov_b32 s45, s44
	s_mul_i32 s40, s54, 0xa000
	s_mul_i32 s41, s54, 0xa00
	s_add_i32 s41, s41, 0x14000
	v_add_u32_e32 v29, s40, v24
	v_add_lshl_u32 v31, v23, v22, 2
	v_mov_b32_e32 v30, s41
	v_add_u32_e32 v31, s41, v31
	v_add_u32_e32 v122, 0x3c0, v31
	v_add_u32_e32 v123, 0x780, v31
	v_add_u32_e32 v124, 0x3c0, v30
	v_add_u32_e32 v125, 0x780, v30
	ds_read_b128 v[44:47], v29 offset:48
	ds_read_b128 v[64:67], v29 offset:1328
	ds_read_b128 v[40:43], v29 offset:32
	ds_read2_b32 v[112:113], v31 offset0:0 offset1:20
	ds_read_b128 v[32:35], v29 offset:0
	ds_read2_b32 v[118:119], v30 offset0:36 offset1:76
	ds_read_b128 v[48:51], v29 offset:64
	ds_read_b128 v[60:63], v29 offset:1312
	ds_read_b128 v[52:55], v29 offset:1280
	ds_read_b128 v[36:39], v29 offset:16
	ds_read_b128 v[68:71], v29 offset:1344
	ds_read_b128 v[56:59], v29 offset:1296
	s_waitcnt lgkmcnt(7)
	v_pk_mul_f32 v[132:133], v[16:17], v[44:45]
	v_pk_mul_f32 v[134:135], v[16:17], v[64:65]
	v_pk_fma_f32 v[132:133], v[18:19], v[46:47], v[132:133]
	v_pk_fma_f32 v[134:135], v[18:19], v[66:67], v[134:135]
	v_pk_mul_f32 v[136:137], v[112:113], v[40:41] op_sel_hi:[0,1]
	v_add_f32_e32 v148, v132, v133
	v_add_f32_e32 v149, v134, v135
	v_pk_mul_f32 v[138:139], v[112:113], v[42:43] op_sel_hi:[0,1]
	v_add_f32_dpp v148, v148, v148 quad_perm:[1,0,3,2] row_mask:0xf bank_mask:0xf bound_ctrl:1
	v_add_f32_dpp v149, v149, v149 quad_perm:[1,0,3,2] row_mask:0xf bank_mask:0xf bound_ctrl:1
	v_pk_fma_f32 v[136:137], v[16:17], v[32:33], v[136:137]
	v_add_f32_dpp v148, v148, v148 quad_perm:[2,3,0,1] row_mask:0xf bank_mask:0xf bound_ctrl:1
	v_add_f32_dpp v149, v149, v149 quad_perm:[2,3,0,1] row_mask:0xf bank_mask:0xf bound_ctrl:1
	v_pk_fma_f32 v[138:139], v[18:19], v[34:35], v[138:139]
	v_add_f32_dpp v148, v148, v148 row_half_mirror row_mask:0xf bank_mask:0xf bound_ctrl:1
	v_add_f32_dpp v149, v149, v149 row_half_mirror row_mask:0xf bank_mask:0xf bound_ctrl:1
	ds_read_b128 v[84:87], v29 offset:2608
	ds_read_b128 v[104:107], v29 offset:3888
	ds_read_b128 v[80:83], v29 offset:2592
	ds_read2_b32 v[114:115], v31 offset0:40 offset1:60
	ds_read_b128 v[72:75], v29 offset:2560
	ds_read_b128 v[88:91], v29 offset:2624
	ds_read_b128 v[100:103], v29 offset:3872
	ds_read_b128 v[92:95], v29 offset:3840
	ds_read_b128 v[76:79], v29 offset:2576
	ds_read_b128 v[108:111], v29 offset:3904
	ds_read_b128 v[96:99], v29 offset:3856
	s_waitcnt lgkmcnt(11)
	v_pk_mul_f32 v[140:141], v[112:113], v[60:61] op_sel:[1,0] op_sel_hi:[1,1]
	v_add_f32_dpp v148, v148, v148 row_mirror row_mask:0xf bank_mask:0xf bound_ctrl:1
	v_add_f32_dpp v149, v149, v149 row_mirror row_mask:0xf bank_mask:0xf bound_ctrl:1
	v_pk_mul_f32 v[142:143], v[112:113], v[62:63] op_sel:[1,0] op_sel_hi:[1,1]
	v_fmac_f32_e32 v149, v112, v118
	v_pk_fma_f32 v[16:17], v[48:49], v[148:149], v[136:137] op_sel_hi:[1,0,1]
	v_pk_fma_f32 v[18:19], v[50:51], v[148:149], v[138:139] op_sel_hi:[1,0,1]
	v_pk_fma_f32 v[140:141], v[16:17], v[52:53], v[140:141]
	v_pk_mul_f32 v[144:145], v[16:17], v[36:37]
	v_pk_fma_f32 v[142:143], v[18:19], v[54:55], v[142:143]
	v_pk_fma_f32 v[144:145], v[18:19], v[38:39], v[144:145]
	v_pk_fma_f32 v[16:17], v[68:69], v[148:149], v[140:141] op_sel:[0,1,0] op_sel_hi:[1,1,1]
	v_pk_fma_f32 v[18:19], v[70:71], v[148:149], v[142:143] op_sel:[0,1,0] op_sel_hi:[1,1,1]
	v_pk_mul_f32 v[146:147], v[16:17], v[56:57]
	v_pk_fma_f32 v[146:147], v[18:19], v[58:59], v[146:147]
	s_waitcnt lgkmcnt(6)
	v_pk_mul_f32 v[132:133], v[16:17], v[84:85]
	v_pk_mul_f32 v[134:135], v[16:17], v[104:105]
	v_add_f32_e32 v200, v144, v145
	v_pk_fma_f32 v[132:133], v[18:19], v[86:87], v[132:133]
	v_pk_fma_f32 v[134:135], v[18:19], v[106:107], v[134:135]
	v_add_f32_e32 v201, v146, v147
	v_pk_mul_f32 v[136:137], v[114:115], v[80:81] op_sel_hi:[0,1]
	v_add_f32_e32 v148, v132, v133
	v_add_f32_e32 v149, v134, v135
	v_pk_mul_f32 v[138:139], v[114:115], v[82:83] op_sel_hi:[0,1]
	v_add_f32_dpp v148, v148, v148 quad_perm:[1,0,3,2] row_mask:0xf bank_mask:0xf bound_ctrl:1
	v_add_f32_dpp v149, v149, v149 quad_perm:[1,0,3,2] row_mask:0xf bank_mask:0xf bound_ctrl:1
	v_pk_fma_f32 v[136:137], v[16:17], v[72:73], v[136:137]
	v_add_f32_dpp v148, v148, v148 quad_perm:[2,3,0,1] row_mask:0xf bank_mask:0xf bound_ctrl:1
	v_add_f32_dpp v149, v149, v149 quad_perm:[2,3,0,1] row_mask:0xf bank_mask:0xf bound_ctrl:1
	v_pk_fma_f32 v[138:139], v[18:19], v[74:75], v[138:139]
	v_add_f32_dpp v148, v148, v148 row_half_mirror row_mask:0xf bank_mask:0xf bound_ctrl:1
	v_add_f32_dpp v149, v149, v149 row_half_mirror row_mask:0xf bank_mask:0xf bound_ctrl:1
	ds_read_b128 v[172:175], v29 offset:5168
	ds_read_b128 v[192:195], v29 offset:6448
	ds_read_b128 v[168:171], v29 offset:5152
	ds_read2_b32 v[116:117], v31 offset0:80 offset1:100
	ds_read_b128 v[160:163], v29 offset:5120
	ds_read2_b32 v[120:121], v30 offset0:116 offset1:156
	ds_read_b128 v[176:179], v29 offset:5184
	ds_read_b128 v[188:191], v29 offset:6432
	ds_read_b128 v[180:183], v29 offset:6400
	ds_read_b128 v[164:167], v29 offset:5136
	ds_read_b128 v[196:199], v29 offset:6464
	ds_read_b128 v[184:187], v29 offset:6416
	s_waitcnt lgkmcnt(12)
	v_pk_mul_f32 v[140:141], v[114:115], v[100:101] op_sel:[1,0] op_sel_hi:[1,1]
	v_add_f32_dpp v148, v148, v148 row_mirror row_mask:0xf bank_mask:0xf bound_ctrl:1
	v_add_f32_dpp v149, v149, v149 row_mirror row_mask:0xf bank_mask:0xf bound_ctrl:1
	v_pk_mul_f32 v[142:143], v[114:115], v[102:103] op_sel:[1,0] op_sel_hi:[1,1]
	v_fmac_f32_e32 v149, v114, v119
	v_pk_fma_f32 v[16:17], v[88:89], v[148:149], v[136:137] op_sel_hi:[1,0,1]
	v_pk_fma_f32 v[18:19], v[90:91], v[148:149], v[138:139] op_sel_hi:[1,0,1]
	v_pk_fma_f32 v[140:141], v[16:17], v[92:93], v[140:141]
	v_pk_mul_f32 v[144:145], v[16:17], v[76:77]
	v_pk_fma_f32 v[142:143], v[18:19], v[94:95], v[142:143]
	v_pk_fma_f32 v[144:145], v[18:19], v[78:79], v[144:145]
	v_pk_fma_f32 v[16:17], v[108:109], v[148:149], v[140:141] op_sel:[0,1,0] op_sel_hi:[1,1,1]
	v_pk_fma_f32 v[18:19], v[110:111], v[148:149], v[142:143] op_sel:[0,1,0] op_sel_hi:[1,1,1]
	v_pk_mul_f32 v[146:147], v[16:17], v[96:97]
	v_pk_fma_f32 v[146:147], v[18:19], v[98:99], v[146:147]
	s_waitcnt lgkmcnt(7)
	v_pk_mul_f32 v[132:133], v[16:17], v[172:173]
	v_pk_mul_f32 v[134:135], v[16:17], v[192:193]
	v_add_f32_e32 v202, v144, v145
	v_pk_fma_f32 v[132:133], v[18:19], v[174:175], v[132:133]
	v_pk_fma_f32 v[134:135], v[18:19], v[194:195], v[134:135]
	v_add_f32_e32 v203, v146, v147
	v_pk_mul_f32 v[136:137], v[116:117], v[168:169] op_sel_hi:[0,1]
	v_add_f32_e32 v148, v132, v133
	v_cndmask_b32_e64 v208, v200, v201, s[10:11]
	v_add_f32_e32 v149, v134, v135
	v_pk_mul_f32 v[138:139], v[116:117], v[170:171] op_sel_hi:[0,1]
	v_cndmask_b32_e64 v209, v201, v200, s[10:11]
	v_add_f32_dpp v148, v148, v148 quad_perm:[1,0,3,2] row_mask:0xf bank_mask:0xf bound_ctrl:1
	v_add_f32_dpp v149, v149, v149 quad_perm:[1,0,3,2] row_mask:0xf bank_mask:0xf bound_ctrl:1
	v_cndmask_b32_e64 v210, v202, v203, s[10:11]
	v_pk_fma_f32 v[136:137], v[16:17], v[160:161], v[136:137]
	v_add_f32_dpp v148, v148, v148 quad_perm:[2,3,0,1] row_mask:0xf bank_mask:0xf bound_ctrl:1
	v_cndmask_b32_e64 v211, v203, v202, s[10:11]
	v_add_f32_dpp v149, v149, v149 quad_perm:[2,3,0,1] row_mask:0xf bank_mask:0xf bound_ctrl:1
	v_pk_fma_f32 v[138:139], v[18:19], v[162:163], v[138:139]
	v_add_f32_dpp v212, v209, v208 quad_perm:[1,0,3,2] row_mask:0xf bank_mask:0xf bound_ctrl:1
	v_add_f32_dpp v148, v148, v148 row_half_mirror row_mask:0xf bank_mask:0xf bound_ctrl:1
	v_add_f32_dpp v149, v149, v149 row_half_mirror row_mask:0xf bank_mask:0xf bound_ctrl:1
	v_add_f32_dpp v213, v211, v210 quad_perm:[1,0,3,2] row_mask:0xf bank_mask:0xf bound_ctrl:1
	ds_read_b128 v[44:47], v29 offset:7728
	ds_read_b128 v[64:67], v29 offset:9008
	ds_read_b128 v[40:43], v29 offset:7712
	ds_read2_b32 v[112:113], v31 offset0:120 offset1:140
	ds_read_b128 v[32:35], v29 offset:7680
	ds_read_b128 v[48:51], v29 offset:7744
	ds_read_b128 v[60:63], v29 offset:8992
	ds_read_b128 v[52:55], v29 offset:8960
	ds_read_b128 v[36:39], v29 offset:7696
	ds_read_b128 v[68:71], v29 offset:9024
	ds_read_b128 v[56:59], v29 offset:8976
	s_waitcnt lgkmcnt(11)
	v_pk_mul_f32 v[140:141], v[116:117], v[188:189] op_sel:[1,0] op_sel_hi:[1,1]
	v_cndmask_b32_e64 v214, v212, v213, s[14:15]
	v_add_f32_dpp v148, v148, v148 row_mirror row_mask:0xf bank_mask:0xf bound_ctrl:1
	v_add_f32_dpp v149, v149, v149 row_mirror row_mask:0xf bank_mask:0xf bound_ctrl:1
	v_cndmask_b32_e64 v215, v213, v212, s[14:15]
	v_pk_mul_f32 v[142:143], v[116:117], v[190:191] op_sel:[1,0] op_sel_hi:[1,1]
	v_fmac_f32_e32 v149, v116, v120
	v_add_f32_dpp v216, v215, v214 quad_perm:[2,3,0,1] row_mask:0xf bank_mask:0xf bound_ctrl:1
	v_pk_fma_f32 v[16:17], v[176:177], v[148:149], v[136:137] op_sel_hi:[1,0,1]
	v_pk_fma_f32 v[18:19], v[178:179], v[148:149], v[138:139] op_sel_hi:[1,0,1]
	v_add_f32_dpp v216, v216, v216 row_ror:8 row_mask:0xf bank_mask:0xf bound_ctrl:1
	v_pk_fma_f32 v[140:141], v[16:17], v[180:181], v[140:141]
	v_pk_mul_f32 v[144:145], v[16:17], v[164:165]
	v_add_f32_dpp v216, v216, v216 row_ror:4 row_mask:0xf bank_mask:0xf bound_ctrl:1
	v_pk_fma_f32 v[142:143], v[18:19], v[182:183], v[142:143]
	v_pk_fma_f32 v[144:145], v[18:19], v[166:167], v[144:145]
	v_cndmask_b32_e64 v28, v28, v216, s[34:35]
	v_pk_fma_f32 v[16:17], v[196:197], v[148:149], v[140:141] op_sel:[0,1,0] op_sel_hi:[1,1,1]
	v_pk_fma_f32 v[18:19], v[198:199], v[148:149], v[142:143] op_sel:[0,1,0] op_sel_hi:[1,1,1]
	v_pk_mul_f32 v[146:147], v[16:17], v[184:185]
	v_pk_fma_f32 v[146:147], v[18:19], v[186:187], v[146:147]
	s_waitcnt lgkmcnt(6)
	v_pk_mul_f32 v[132:133], v[16:17], v[44:45]
	v_pk_mul_f32 v[134:135], v[16:17], v[64:65]
	v_add_f32_e32 v204, v144, v145
	v_pk_fma_f32 v[132:133], v[18:19], v[46:47], v[132:133]
	v_pk_fma_f32 v[134:135], v[18:19], v[66:67], v[134:135]
	v_add_f32_e32 v205, v146, v147
	v_pk_mul_f32 v[136:137], v[112:113], v[40:41] op_sel_hi:[0,1]
	v_add_f32_e32 v148, v132, v133
	v_add_f32_e32 v149, v134, v135
	v_pk_mul_f32 v[138:139], v[112:113], v[42:43] op_sel_hi:[0,1]
	v_add_f32_dpp v148, v148, v148 quad_perm:[1,0,3,2] row_mask:0xf bank_mask:0xf bound_ctrl:1
	v_add_f32_dpp v149, v149, v149 quad_perm:[1,0,3,2] row_mask:0xf bank_mask:0xf bound_ctrl:1
	v_pk_fma_f32 v[136:137], v[16:17], v[32:33], v[136:137]
	v_add_f32_dpp v148, v148, v148 quad_perm:[2,3,0,1] row_mask:0xf bank_mask:0xf bound_ctrl:1
	v_add_f32_dpp v149, v149, v149 quad_perm:[2,3,0,1] row_mask:0xf bank_mask:0xf bound_ctrl:1
	v_pk_fma_f32 v[138:139], v[18:19], v[34:35], v[138:139]
	v_add_f32_dpp v148, v148, v148 row_half_mirror row_mask:0xf bank_mask:0xf bound_ctrl:1
	v_add_f32_dpp v149, v149, v149 row_half_mirror row_mask:0xf bank_mask:0xf bound_ctrl:1
	ds_read_b128 v[84:87], v29 offset:10288
	ds_read_b128 v[104:107], v29 offset:11568
	ds_read_b128 v[80:83], v29 offset:10272
	ds_read2_b32 v[114:115], v31 offset0:160 offset1:180
	ds_read_b128 v[72:75], v29 offset:10240
	ds_read2_b32 v[118:119], v30 offset0:196 offset1:236
	ds_read_b128 v[88:91], v29 offset:10304
	ds_read_b128 v[100:103], v29 offset:11552
	ds_read_b128 v[92:95], v29 offset:11520
	ds_read_b128 v[76:79], v29 offset:10256
	ds_read_b128 v[108:111], v29 offset:11584
	ds_read_b128 v[96:99], v29 offset:11536
	s_waitcnt lgkmcnt(12)
	v_pk_mul_f32 v[140:141], v[112:113], v[60:61] op_sel:[1,0] op_sel_hi:[1,1]
	v_add_f32_dpp v148, v148, v148 row_mirror row_mask:0xf bank_mask:0xf bound_ctrl:1
	v_add_f32_dpp v149, v149, v149 row_mirror row_mask:0xf bank_mask:0xf bound_ctrl:1
	v_pk_mul_f32 v[142:143], v[112:113], v[62:63] op_sel:[1,0] op_sel_hi:[1,1]
	v_fmac_f32_e32 v149, v112, v121
	v_pk_fma_f32 v[16:17], v[48:49], v[148:149], v[136:137] op_sel_hi:[1,0,1]
	v_pk_fma_f32 v[18:19], v[50:51], v[148:149], v[138:139] op_sel_hi:[1,0,1]
	v_pk_fma_f32 v[140:141], v[16:17], v[52:53], v[140:141]
	v_pk_mul_f32 v[144:145], v[16:17], v[36:37]
	v_pk_fma_f32 v[142:143], v[18:19], v[54:55], v[142:143]
	v_pk_fma_f32 v[144:145], v[18:19], v[38:39], v[144:145]
	v_pk_fma_f32 v[16:17], v[68:69], v[148:149], v[140:141] op_sel:[0,1,0] op_sel_hi:[1,1,1]
	v_pk_fma_f32 v[18:19], v[70:71], v[148:149], v[142:143] op_sel:[0,1,0] op_sel_hi:[1,1,1]
	v_pk_mul_f32 v[146:147], v[16:17], v[56:57]
	v_pk_fma_f32 v[146:147], v[18:19], v[58:59], v[146:147]
	s_waitcnt lgkmcnt(7)
	v_pk_mul_f32 v[132:133], v[16:17], v[84:85]
	v_pk_mul_f32 v[134:135], v[16:17], v[104:105]
	v_add_f32_e32 v206, v144, v145
	v_pk_fma_f32 v[132:133], v[18:19], v[86:87], v[132:133]
	v_pk_fma_f32 v[134:135], v[18:19], v[106:107], v[134:135]
	v_add_f32_e32 v207, v146, v147
	v_pk_mul_f32 v[136:137], v[114:115], v[80:81] op_sel_hi:[0,1]
	v_add_f32_e32 v148, v132, v133
	v_cndmask_b32_e64 v208, v204, v205, s[10:11]
	v_add_f32_e32 v149, v134, v135
	v_pk_mul_f32 v[138:139], v[114:115], v[82:83] op_sel_hi:[0,1]
	v_cndmask_b32_e64 v209, v205, v204, s[10:11]
	v_add_f32_dpp v148, v148, v148 quad_perm:[1,0,3,2] row_mask:0xf bank_mask:0xf bound_ctrl:1
	v_add_f32_dpp v149, v149, v149 quad_perm:[1,0,3,2] row_mask:0xf bank_mask:0xf bound_ctrl:1
	v_cndmask_b32_e64 v210, v206, v207, s[10:11]
	v_pk_fma_f32 v[136:137], v[16:17], v[72:73], v[136:137]
	v_add_f32_dpp v148, v148, v148 quad_perm:[2,3,0,1] row_mask:0xf bank_mask:0xf bound_ctrl:1
	v_cndmask_b32_e64 v211, v207, v206, s[10:11]
	v_add_f32_dpp v149, v149, v149 quad_perm:[2,3,0,1] row_mask:0xf bank_mask:0xf bound_ctrl:1
	v_pk_fma_f32 v[138:139], v[18:19], v[74:75], v[138:139]
	v_add_f32_dpp v212, v209, v208 quad_perm:[1,0,3,2] row_mask:0xf bank_mask:0xf bound_ctrl:1
	v_add_f32_dpp v148, v148, v148 row_half_mirror row_mask:0xf bank_mask:0xf bound_ctrl:1
	v_add_f32_dpp v149, v149, v149 row_half_mirror row_mask:0xf bank_mask:0xf bound_ctrl:1
	v_add_f32_dpp v213, v211, v210 quad_perm:[1,0,3,2] row_mask:0xf bank_mask:0xf bound_ctrl:1
	ds_read_b128 v[172:175], v29 offset:12848
	ds_read_b128 v[192:195], v29 offset:14128
	ds_read_b128 v[168:171], v29 offset:12832
	ds_read2_b32 v[116:117], v31 offset0:200 offset1:220
	ds_read_b128 v[160:163], v29 offset:12800
	ds_read_b128 v[176:179], v29 offset:12864
	ds_read_b128 v[188:191], v29 offset:14112
	ds_read_b128 v[180:183], v29 offset:14080
	ds_read_b128 v[164:167], v29 offset:12816
	ds_read_b128 v[196:199], v29 offset:14144
	ds_read_b128 v[184:187], v29 offset:14096
	s_waitcnt lgkmcnt(11)
	v_pk_mul_f32 v[140:141], v[114:115], v[100:101] op_sel:[1,0] op_sel_hi:[1,1]
	v_cndmask_b32_e64 v214, v212, v213, s[14:15]
	v_add_f32_dpp v148, v148, v148 row_mirror row_mask:0xf bank_mask:0xf bound_ctrl:1
	v_add_f32_dpp v149, v149, v149 row_mirror row_mask:0xf bank_mask:0xf bound_ctrl:1
	v_cndmask_b32_e64 v215, v213, v212, s[14:15]
	v_pk_mul_f32 v[142:143], v[114:115], v[102:103] op_sel:[1,0] op_sel_hi:[1,1]
	v_fmac_f32_e32 v149, v114, v118
	v_add_f32_dpp v216, v215, v214 quad_perm:[2,3,0,1] row_mask:0xf bank_mask:0xf bound_ctrl:1
	v_pk_fma_f32 v[16:17], v[88:89], v[148:149], v[136:137] op_sel_hi:[1,0,1]
	v_pk_fma_f32 v[18:19], v[90:91], v[148:149], v[138:139] op_sel_hi:[1,0,1]
	v_add_f32_dpp v216, v216, v216 row_ror:8 row_mask:0xf bank_mask:0xf bound_ctrl:1
	v_pk_fma_f32 v[140:141], v[16:17], v[92:93], v[140:141]
	v_pk_mul_f32 v[144:145], v[16:17], v[76:77]
	v_add_f32_dpp v216, v216, v216 row_ror:4 row_mask:0xf bank_mask:0xf bound_ctrl:1
	v_pk_fma_f32 v[142:143], v[18:19], v[94:95], v[142:143]
	v_pk_fma_f32 v[144:145], v[18:19], v[78:79], v[144:145]
	v_cndmask_b32_e64 v28, v28, v216, s[36:37]
	v_pk_fma_f32 v[16:17], v[108:109], v[148:149], v[140:141] op_sel:[0,1,0] op_sel_hi:[1,1,1]
	v_pk_fma_f32 v[18:19], v[110:111], v[148:149], v[142:143] op_sel:[0,1,0] op_sel_hi:[1,1,1]
	v_pk_mul_f32 v[146:147], v[16:17], v[96:97]
	v_pk_fma_f32 v[146:147], v[18:19], v[98:99], v[146:147]
	s_waitcnt lgkmcnt(6)
	v_pk_mul_f32 v[132:133], v[16:17], v[172:173]
	v_pk_mul_f32 v[134:135], v[16:17], v[192:193]
	v_add_f32_e32 v200, v144, v145
	v_pk_fma_f32 v[132:133], v[18:19], v[174:175], v[132:133]
	v_pk_fma_f32 v[134:135], v[18:19], v[194:195], v[134:135]
	v_add_f32_e32 v201, v146, v147
	v_pk_mul_f32 v[136:137], v[116:117], v[168:169] op_sel_hi:[0,1]
	v_add_f32_e32 v148, v132, v133
	v_add_f32_e32 v149, v134, v135
	v_pk_mul_f32 v[138:139], v[116:117], v[170:171] op_sel_hi:[0,1]
	v_add_f32_dpp v148, v148, v148 quad_perm:[1,0,3,2] row_mask:0xf bank_mask:0xf bound_ctrl:1
	v_add_f32_dpp v149, v149, v149 quad_perm:[1,0,3,2] row_mask:0xf bank_mask:0xf bound_ctrl:1
	v_pk_fma_f32 v[136:137], v[16:17], v[160:161], v[136:137]
	v_add_f32_dpp v148, v148, v148 quad_perm:[2,3,0,1] row_mask:0xf bank_mask:0xf bound_ctrl:1
	v_add_f32_dpp v149, v149, v149 quad_perm:[2,3,0,1] row_mask:0xf bank_mask:0xf bound_ctrl:1
	v_pk_fma_f32 v[138:139], v[18:19], v[162:163], v[138:139]
	v_add_f32_dpp v148, v148, v148 row_half_mirror row_mask:0xf bank_mask:0xf bound_ctrl:1
	v_add_f32_dpp v149, v149, v149 row_half_mirror row_mask:0xf bank_mask:0xf bound_ctrl:1
	ds_read_b128 v[44:47], v29 offset:15408
	ds_read_b128 v[64:67], v29 offset:16688
	ds_read_b128 v[40:43], v29 offset:15392
	ds_read2_b32 v[112:113], v122 offset0:0 offset1:20
	ds_read_b128 v[32:35], v29 offset:15360
	ds_read2_b32 v[120:121], v124 offset0:36 offset1:76
	ds_read_b128 v[48:51], v29 offset:15424
	ds_read_b128 v[60:63], v29 offset:16672
	ds_read_b128 v[52:55], v29 offset:16640
	ds_read_b128 v[36:39], v29 offset:15376
	ds_read_b128 v[68:71], v29 offset:16704
	ds_read_b128 v[56:59], v29 offset:16656
	s_waitcnt lgkmcnt(12)
	v_pk_mul_f32 v[140:141], v[116:117], v[188:189] op_sel:[1,0] op_sel_hi:[1,1]
	v_add_f32_dpp v148, v148, v148 row_mirror row_mask:0xf bank_mask:0xf bound_ctrl:1
	v_add_f32_dpp v149, v149, v149 row_mirror row_mask:0xf bank_mask:0xf bound_ctrl:1
	v_pk_mul_f32 v[142:143], v[116:117], v[190:191] op_sel:[1,0] op_sel_hi:[1,1]
	v_fmac_f32_e32 v149, v116, v119
	v_pk_fma_f32 v[16:17], v[176:177], v[148:149], v[136:137] op_sel_hi:[1,0,1]
	v_pk_fma_f32 v[18:19], v[178:179], v[148:149], v[138:139] op_sel_hi:[1,0,1]
	v_pk_fma_f32 v[140:141], v[16:17], v[180:181], v[140:141]
	v_pk_mul_f32 v[144:145], v[16:17], v[164:165]
	v_pk_fma_f32 v[142:143], v[18:19], v[182:183], v[142:143]
	v_pk_fma_f32 v[144:145], v[18:19], v[166:167], v[144:145]
	v_pk_fma_f32 v[16:17], v[196:197], v[148:149], v[140:141] op_sel:[0,1,0] op_sel_hi:[1,1,1]
	v_pk_fma_f32 v[18:19], v[198:199], v[148:149], v[142:143] op_sel:[0,1,0] op_sel_hi:[1,1,1]
	v_pk_mul_f32 v[146:147], v[16:17], v[184:185]
	v_pk_fma_f32 v[146:147], v[18:19], v[186:187], v[146:147]
	s_waitcnt lgkmcnt(7)
	v_pk_mul_f32 v[132:133], v[16:17], v[44:45]
	v_pk_mul_f32 v[134:135], v[16:17], v[64:65]
	v_add_f32_e32 v202, v144, v145
	v_pk_fma_f32 v[132:133], v[18:19], v[46:47], v[132:133]
	v_pk_fma_f32 v[134:135], v[18:19], v[66:67], v[134:135]
	v_add_f32_e32 v203, v146, v147
	v_pk_mul_f32 v[136:137], v[112:113], v[40:41] op_sel_hi:[0,1]
	v_add_f32_e32 v148, v132, v133
	v_cndmask_b32_e64 v208, v200, v201, s[10:11]
	v_add_f32_e32 v149, v134, v135
	v_pk_mul_f32 v[138:139], v[112:113], v[42:43] op_sel_hi:[0,1]
	v_cndmask_b32_e64 v209, v201, v200, s[10:11]
	v_add_f32_dpp v148, v148, v148 quad_perm:[1,0,3,2] row_mask:0xf bank_mask:0xf bound_ctrl:1
	v_add_f32_dpp v149, v149, v149 quad_perm:[1,0,3,2] row_mask:0xf bank_mask:0xf bound_ctrl:1
	v_cndmask_b32_e64 v210, v202, v203, s[10:11]
	v_pk_fma_f32 v[136:137], v[16:17], v[32:33], v[136:137]
	v_add_f32_dpp v148, v148, v148 quad_perm:[2,3,0,1] row_mask:0xf bank_mask:0xf bound_ctrl:1
	v_cndmask_b32_e64 v211, v203, v202, s[10:11]
	v_add_f32_dpp v149, v149, v149 quad_perm:[2,3,0,1] row_mask:0xf bank_mask:0xf bound_ctrl:1
	v_pk_fma_f32 v[138:139], v[18:19], v[34:35], v[138:139]
	v_add_f32_dpp v212, v209, v208 quad_perm:[1,0,3,2] row_mask:0xf bank_mask:0xf bound_ctrl:1
	v_add_f32_dpp v148, v148, v148 row_half_mirror row_mask:0xf bank_mask:0xf bound_ctrl:1
	v_add_f32_dpp v149, v149, v149 row_half_mirror row_mask:0xf bank_mask:0xf bound_ctrl:1
	v_add_f32_dpp v213, v211, v210 quad_perm:[1,0,3,2] row_mask:0xf bank_mask:0xf bound_ctrl:1
	ds_read_b128 v[84:87], v29 offset:17968
	ds_read_b128 v[104:107], v29 offset:19248
	ds_read_b128 v[80:83], v29 offset:17952
	ds_read2_b32 v[114:115], v122 offset0:40 offset1:60
	ds_read_b128 v[72:75], v29 offset:17920
	ds_read_b128 v[88:91], v29 offset:17984
	ds_read_b128 v[100:103], v29 offset:19232
	ds_read_b128 v[92:95], v29 offset:19200
	ds_read_b128 v[76:79], v29 offset:17936
	ds_read_b128 v[108:111], v29 offset:19264
	ds_read_b128 v[96:99], v29 offset:19216
	s_waitcnt lgkmcnt(11)
	v_pk_mul_f32 v[140:141], v[112:113], v[60:61] op_sel:[1,0] op_sel_hi:[1,1]
	v_cndmask_b32_e64 v214, v212, v213, s[14:15]
	v_add_f32_dpp v148, v148, v148 row_mirror row_mask:0xf bank_mask:0xf bound_ctrl:1
	v_add_f32_dpp v149, v149, v149 row_mirror row_mask:0xf bank_mask:0xf bound_ctrl:1
	v_cndmask_b32_e64 v215, v213, v212, s[14:15]
	v_pk_mul_f32 v[142:143], v[112:113], v[62:63] op_sel:[1,0] op_sel_hi:[1,1]
	v_fmac_f32_e32 v149, v112, v120
	v_add_f32_dpp v216, v215, v214 quad_perm:[2,3,0,1] row_mask:0xf bank_mask:0xf bound_ctrl:1
	v_pk_fma_f32 v[16:17], v[48:49], v[148:149], v[136:137] op_sel_hi:[1,0,1]
	v_pk_fma_f32 v[18:19], v[50:51], v[148:149], v[138:139] op_sel_hi:[1,0,1]
	v_add_f32_dpp v216, v216, v216 row_ror:8 row_mask:0xf bank_mask:0xf bound_ctrl:1
	v_pk_fma_f32 v[140:141], v[16:17], v[52:53], v[140:141]
	v_pk_mul_f32 v[144:145], v[16:17], v[36:37]
	v_add_f32_dpp v216, v216, v216 row_ror:4 row_mask:0xf bank_mask:0xf bound_ctrl:1
	v_pk_fma_f32 v[142:143], v[18:19], v[54:55], v[142:143]
	v_pk_fma_f32 v[144:145], v[18:19], v[38:39], v[144:145]
	v_cndmask_b32_e64 v28, v28, v216, s[42:43]
	v_pk_fma_f32 v[16:17], v[68:69], v[148:149], v[140:141] op_sel:[0,1,0] op_sel_hi:[1,1,1]
	v_pk_fma_f32 v[18:19], v[70:71], v[148:149], v[142:143] op_sel:[0,1,0] op_sel_hi:[1,1,1]
	v_pk_mul_f32 v[146:147], v[16:17], v[56:57]
	v_pk_fma_f32 v[146:147], v[18:19], v[58:59], v[146:147]
	s_waitcnt lgkmcnt(6)
	v_pk_mul_f32 v[132:133], v[16:17], v[84:85]
	v_pk_mul_f32 v[134:135], v[16:17], v[104:105]
	v_add_f32_e32 v204, v144, v145
	v_pk_fma_f32 v[132:133], v[18:19], v[86:87], v[132:133]
	v_pk_fma_f32 v[134:135], v[18:19], v[106:107], v[134:135]
	v_add_f32_e32 v205, v146, v147
	v_pk_mul_f32 v[136:137], v[114:115], v[80:81] op_sel_hi:[0,1]
	v_add_f32_e32 v148, v132, v133
	v_add_f32_e32 v149, v134, v135
	v_pk_mul_f32 v[138:139], v[114:115], v[82:83] op_sel_hi:[0,1]
	v_add_f32_dpp v148, v148, v148 quad_perm:[1,0,3,2] row_mask:0xf bank_mask:0xf bound_ctrl:1
	v_add_f32_dpp v149, v149, v149 quad_perm:[1,0,3,2] row_mask:0xf bank_mask:0xf bound_ctrl:1
	v_pk_fma_f32 v[136:137], v[16:17], v[72:73], v[136:137]
	v_add_f32_dpp v148, v148, v148 quad_perm:[2,3,0,1] row_mask:0xf bank_mask:0xf bound_ctrl:1
	v_add_f32_dpp v149, v149, v149 quad_perm:[2,3,0,1] row_mask:0xf bank_mask:0xf bound_ctrl:1
	v_pk_fma_f32 v[138:139], v[18:19], v[74:75], v[138:139]
	v_add_f32_dpp v148, v148, v148 row_half_mirror row_mask:0xf bank_mask:0xf bound_ctrl:1
	v_add_f32_dpp v149, v149, v149 row_half_mirror row_mask:0xf bank_mask:0xf bound_ctrl:1
	ds_read_b128 v[172:175], v29 offset:20528
	ds_read_b128 v[192:195], v29 offset:21808
	ds_read_b128 v[168:171], v29 offset:20512
	ds_read2_b32 v[116:117], v122 offset0:80 offset1:100
	ds_read_b128 v[160:163], v29 offset:20480
	ds_read2_b32 v[118:119], v124 offset0:116 offset1:156
	ds_read_b128 v[176:179], v29 offset:20544
	ds_read_b128 v[188:191], v29 offset:21792
	ds_read_b128 v[180:183], v29 offset:21760
	ds_read_b128 v[164:167], v29 offset:20496
	ds_read_b128 v[196:199], v29 offset:21824
	ds_read_b128 v[184:187], v29 offset:21776
	s_waitcnt lgkmcnt(12)
	v_pk_mul_f32 v[140:141], v[114:115], v[100:101] op_sel:[1,0] op_sel_hi:[1,1]
	v_add_f32_dpp v148, v148, v148 row_mirror row_mask:0xf bank_mask:0xf bound_ctrl:1
	v_add_f32_dpp v149, v149, v149 row_mirror row_mask:0xf bank_mask:0xf bound_ctrl:1
	v_pk_mul_f32 v[142:143], v[114:115], v[102:103] op_sel:[1,0] op_sel_hi:[1,1]
	v_fmac_f32_e32 v149, v114, v121
	v_pk_fma_f32 v[16:17], v[88:89], v[148:149], v[136:137] op_sel_hi:[1,0,1]
	v_pk_fma_f32 v[18:19], v[90:91], v[148:149], v[138:139] op_sel_hi:[1,0,1]
	v_pk_fma_f32 v[140:141], v[16:17], v[92:93], v[140:141]
	v_pk_mul_f32 v[144:145], v[16:17], v[76:77]
	v_pk_fma_f32 v[142:143], v[18:19], v[94:95], v[142:143]
	v_pk_fma_f32 v[144:145], v[18:19], v[78:79], v[144:145]
	v_pk_fma_f32 v[16:17], v[108:109], v[148:149], v[140:141] op_sel:[0,1,0] op_sel_hi:[1,1,1]
	v_pk_fma_f32 v[18:19], v[110:111], v[148:149], v[142:143] op_sel:[0,1,0] op_sel_hi:[1,1,1]
	v_pk_mul_f32 v[146:147], v[16:17], v[96:97]
	v_pk_fma_f32 v[146:147], v[18:19], v[98:99], v[146:147]
	s_waitcnt lgkmcnt(7)
	v_pk_mul_f32 v[132:133], v[16:17], v[172:173]
	v_pk_mul_f32 v[134:135], v[16:17], v[192:193]
	v_add_f32_e32 v206, v144, v145
	v_pk_fma_f32 v[132:133], v[18:19], v[174:175], v[132:133]
	v_pk_fma_f32 v[134:135], v[18:19], v[194:195], v[134:135]
	v_add_f32_e32 v207, v146, v147
	v_pk_mul_f32 v[136:137], v[116:117], v[168:169] op_sel_hi:[0,1]
	v_add_f32_e32 v148, v132, v133
	v_cndmask_b32_e64 v208, v204, v205, s[10:11]
	v_add_f32_e32 v149, v134, v135
	v_pk_mul_f32 v[138:139], v[116:117], v[170:171] op_sel_hi:[0,1]
	v_cndmask_b32_e64 v209, v205, v204, s[10:11]
	v_add_f32_dpp v148, v148, v148 quad_perm:[1,0,3,2] row_mask:0xf bank_mask:0xf bound_ctrl:1
	v_add_f32_dpp v149, v149, v149 quad_perm:[1,0,3,2] row_mask:0xf bank_mask:0xf bound_ctrl:1
	v_cndmask_b32_e64 v210, v206, v207, s[10:11]
	v_pk_fma_f32 v[136:137], v[16:17], v[160:161], v[136:137]
	v_add_f32_dpp v148, v148, v148 quad_perm:[2,3,0,1] row_mask:0xf bank_mask:0xf bound_ctrl:1
	v_cndmask_b32_e64 v211, v207, v206, s[10:11]
	v_add_f32_dpp v149, v149, v149 quad_perm:[2,3,0,1] row_mask:0xf bank_mask:0xf bound_ctrl:1
	v_pk_fma_f32 v[138:139], v[18:19], v[162:163], v[138:139]
	v_add_f32_dpp v212, v209, v208 quad_perm:[1,0,3,2] row_mask:0xf bank_mask:0xf bound_ctrl:1
	v_add_f32_dpp v148, v148, v148 row_half_mirror row_mask:0xf bank_mask:0xf bound_ctrl:1
	v_add_f32_dpp v149, v149, v149 row_half_mirror row_mask:0xf bank_mask:0xf bound_ctrl:1
	v_add_f32_dpp v213, v211, v210 quad_perm:[1,0,3,2] row_mask:0xf bank_mask:0xf bound_ctrl:1
	ds_read_b128 v[44:47], v29 offset:23088
	ds_read_b128 v[64:67], v29 offset:24368
	ds_read_b128 v[40:43], v29 offset:23072
	ds_read2_b32 v[112:113], v122 offset0:120 offset1:140
	ds_read_b128 v[32:35], v29 offset:23040
	ds_read_b128 v[48:51], v29 offset:23104
	ds_read_b128 v[60:63], v29 offset:24352
	ds_read_b128 v[52:55], v29 offset:24320
	ds_read_b128 v[36:39], v29 offset:23056
	ds_read_b128 v[68:71], v29 offset:24384
	ds_read_b128 v[56:59], v29 offset:24336
	s_waitcnt lgkmcnt(11)
	v_pk_mul_f32 v[140:141], v[116:117], v[188:189] op_sel:[1,0] op_sel_hi:[1,1]
	v_cndmask_b32_e64 v214, v212, v213, s[14:15]
	v_add_f32_dpp v148, v148, v148 row_mirror row_mask:0xf bank_mask:0xf bound_ctrl:1
	v_add_f32_dpp v149, v149, v149 row_mirror row_mask:0xf bank_mask:0xf bound_ctrl:1
	v_cndmask_b32_e64 v215, v213, v212, s[14:15]
	v_pk_mul_f32 v[142:143], v[116:117], v[190:191] op_sel:[1,0] op_sel_hi:[1,1]
	v_fmac_f32_e32 v149, v116, v118
	v_add_f32_dpp v216, v215, v214 quad_perm:[2,3,0,1] row_mask:0xf bank_mask:0xf bound_ctrl:1
	v_pk_fma_f32 v[16:17], v[176:177], v[148:149], v[136:137] op_sel_hi:[1,0,1]
	v_pk_fma_f32 v[18:19], v[178:179], v[148:149], v[138:139] op_sel_hi:[1,0,1]
	v_add_f32_dpp v216, v216, v216 row_ror:8 row_mask:0xf bank_mask:0xf bound_ctrl:1
	v_pk_fma_f32 v[140:141], v[16:17], v[180:181], v[140:141]
	v_pk_mul_f32 v[144:145], v[16:17], v[164:165]
	v_add_f32_dpp v216, v216, v216 row_ror:4 row_mask:0xf bank_mask:0xf bound_ctrl:1
	v_pk_fma_f32 v[142:143], v[18:19], v[182:183], v[142:143]
	v_pk_fma_f32 v[144:145], v[18:19], v[166:167], v[144:145]
	v_cndmask_b32_e64 v28, v28, v216, s[44:45]
	v_pk_fma_f32 v[16:17], v[196:197], v[148:149], v[140:141] op_sel:[0,1,0] op_sel_hi:[1,1,1]
	v_pk_fma_f32 v[18:19], v[198:199], v[148:149], v[142:143] op_sel:[0,1,0] op_sel_hi:[1,1,1]
	v_add_co_u32_e32 v218, vcc, s59, v12
	v_pk_mul_f32 v[146:147], v[16:17], v[184:185]
	v_pk_fma_f32 v[146:147], v[18:19], v[186:187], v[146:147]
	s_nop 1
	v_addc_co_u32_e32 v219, vcc, 0, v13, vcc
	global_store_dword v[218:219], v28, off
	s_waitcnt lgkmcnt(6)
	v_pk_mul_f32 v[132:133], v[16:17], v[44:45]
	v_pk_mul_f32 v[134:135], v[16:17], v[64:65]
	v_add_f32_e32 v200, v144, v145
	v_pk_fma_f32 v[132:133], v[18:19], v[46:47], v[132:133]
	v_pk_fma_f32 v[134:135], v[18:19], v[66:67], v[134:135]
	v_add_f32_e32 v201, v146, v147
	v_pk_mul_f32 v[136:137], v[112:113], v[40:41] op_sel_hi:[0,1]
	v_add_f32_e32 v148, v132, v133
	v_add_f32_e32 v149, v134, v135
	v_pk_mul_f32 v[138:139], v[112:113], v[42:43] op_sel_hi:[0,1]
	v_add_f32_dpp v148, v148, v148 quad_perm:[1,0,3,2] row_mask:0xf bank_mask:0xf bound_ctrl:1
	v_add_f32_dpp v149, v149, v149 quad_perm:[1,0,3,2] row_mask:0xf bank_mask:0xf bound_ctrl:1
	v_pk_fma_f32 v[136:137], v[16:17], v[32:33], v[136:137]
	v_add_f32_dpp v148, v148, v148 quad_perm:[2,3,0,1] row_mask:0xf bank_mask:0xf bound_ctrl:1
	v_add_f32_dpp v149, v149, v149 quad_perm:[2,3,0,1] row_mask:0xf bank_mask:0xf bound_ctrl:1
	v_pk_fma_f32 v[138:139], v[18:19], v[34:35], v[138:139]
	v_add_f32_dpp v148, v148, v148 row_half_mirror row_mask:0xf bank_mask:0xf bound_ctrl:1
	v_add_f32_dpp v149, v149, v149 row_half_mirror row_mask:0xf bank_mask:0xf bound_ctrl:1
	ds_read_b128 v[84:87], v29 offset:25648
	ds_read_b128 v[104:107], v29 offset:26928
	ds_read_b128 v[80:83], v29 offset:25632
	ds_read2_b32 v[114:115], v122 offset0:160 offset1:180
	ds_read_b128 v[72:75], v29 offset:25600
	ds_read2_b32 v[120:121], v124 offset0:196 offset1:236
	ds_read_b128 v[88:91], v29 offset:25664
	ds_read_b128 v[100:103], v29 offset:26912
	ds_read_b128 v[92:95], v29 offset:26880
	ds_read_b128 v[76:79], v29 offset:25616
	ds_read_b128 v[108:111], v29 offset:26944
	ds_read_b128 v[96:99], v29 offset:26896
	s_waitcnt lgkmcnt(12)
	v_pk_mul_f32 v[140:141], v[112:113], v[60:61] op_sel:[1,0] op_sel_hi:[1,1]
	v_add_f32_dpp v148, v148, v148 row_mirror row_mask:0xf bank_mask:0xf bound_ctrl:1
	v_add_f32_dpp v149, v149, v149 row_mirror row_mask:0xf bank_mask:0xf bound_ctrl:1
	v_pk_mul_f32 v[142:143], v[112:113], v[62:63] op_sel:[1,0] op_sel_hi:[1,1]
	v_fmac_f32_e32 v149, v112, v119
	v_pk_fma_f32 v[16:17], v[48:49], v[148:149], v[136:137] op_sel_hi:[1,0,1]
	v_pk_fma_f32 v[18:19], v[50:51], v[148:149], v[138:139] op_sel_hi:[1,0,1]
	v_pk_fma_f32 v[140:141], v[16:17], v[52:53], v[140:141]
	v_pk_mul_f32 v[144:145], v[16:17], v[36:37]
	v_pk_fma_f32 v[142:143], v[18:19], v[54:55], v[142:143]
	v_pk_fma_f32 v[144:145], v[18:19], v[38:39], v[144:145]
	v_pk_fma_f32 v[16:17], v[68:69], v[148:149], v[140:141] op_sel:[0,1,0] op_sel_hi:[1,1,1]
	v_pk_fma_f32 v[18:19], v[70:71], v[148:149], v[142:143] op_sel:[0,1,0] op_sel_hi:[1,1,1]
	v_pk_mul_f32 v[146:147], v[16:17], v[56:57]
	v_pk_fma_f32 v[146:147], v[18:19], v[58:59], v[146:147]
	s_waitcnt lgkmcnt(7)
	v_pk_mul_f32 v[132:133], v[16:17], v[84:85]
	v_pk_mul_f32 v[134:135], v[16:17], v[104:105]
	v_add_f32_e32 v202, v144, v145
	v_pk_fma_f32 v[132:133], v[18:19], v[86:87], v[132:133]
	v_pk_fma_f32 v[134:135], v[18:19], v[106:107], v[134:135]
	v_add_f32_e32 v203, v146, v147
	v_pk_mul_f32 v[136:137], v[114:115], v[80:81] op_sel_hi:[0,1]
	v_add_f32_e32 v148, v132, v133
	v_cndmask_b32_e64 v208, v200, v201, s[10:11]
	v_add_f32_e32 v149, v134, v135
	v_pk_mul_f32 v[138:139], v[114:115], v[82:83] op_sel_hi:[0,1]
	v_cndmask_b32_e64 v209, v201, v200, s[10:11]
	v_add_f32_dpp v148, v148, v148 quad_perm:[1,0,3,2] row_mask:0xf bank_mask:0xf bound_ctrl:1
	v_add_f32_dpp v149, v149, v149 quad_perm:[1,0,3,2] row_mask:0xf bank_mask:0xf bound_ctrl:1
	v_cndmask_b32_e64 v210, v202, v203, s[10:11]
	v_pk_fma_f32 v[136:137], v[16:17], v[72:73], v[136:137]
	v_add_f32_dpp v148, v148, v148 quad_perm:[2,3,0,1] row_mask:0xf bank_mask:0xf bound_ctrl:1
	v_cndmask_b32_e64 v211, v203, v202, s[10:11]
	v_add_f32_dpp v149, v149, v149 quad_perm:[2,3,0,1] row_mask:0xf bank_mask:0xf bound_ctrl:1
	v_pk_fma_f32 v[138:139], v[18:19], v[74:75], v[138:139]
	v_add_f32_dpp v212, v209, v208 quad_perm:[1,0,3,2] row_mask:0xf bank_mask:0xf bound_ctrl:1
	v_add_f32_dpp v148, v148, v148 row_half_mirror row_mask:0xf bank_mask:0xf bound_ctrl:1
	v_add_f32_dpp v149, v149, v149 row_half_mirror row_mask:0xf bank_mask:0xf bound_ctrl:1
	v_add_f32_dpp v213, v211, v210 quad_perm:[1,0,3,2] row_mask:0xf bank_mask:0xf bound_ctrl:1
	ds_read_b128 v[172:175], v29 offset:28208
	ds_read_b128 v[192:195], v29 offset:29488
	ds_read_b128 v[168:171], v29 offset:28192
	ds_read2_b32 v[116:117], v122 offset0:200 offset1:220
	ds_read_b128 v[160:163], v29 offset:28160
	ds_read_b128 v[176:179], v29 offset:28224
	ds_read_b128 v[188:191], v29 offset:29472
	ds_read_b128 v[180:183], v29 offset:29440
	ds_read_b128 v[164:167], v29 offset:28176
	ds_read_b128 v[196:199], v29 offset:29504
	ds_read_b128 v[184:187], v29 offset:29456
	s_waitcnt lgkmcnt(11)
	v_pk_mul_f32 v[140:141], v[114:115], v[100:101] op_sel:[1,0] op_sel_hi:[1,1]
	v_cndmask_b32_e64 v214, v212, v213, s[14:15]
	v_add_f32_dpp v148, v148, v148 row_mirror row_mask:0xf bank_mask:0xf bound_ctrl:1
	v_add_f32_dpp v149, v149, v149 row_mirror row_mask:0xf bank_mask:0xf bound_ctrl:1
	v_cndmask_b32_e64 v215, v213, v212, s[14:15]
	v_pk_mul_f32 v[142:143], v[114:115], v[102:103] op_sel:[1,0] op_sel_hi:[1,1]
	v_fmac_f32_e32 v149, v114, v120
	v_add_f32_dpp v216, v215, v214 quad_perm:[2,3,0,1] row_mask:0xf bank_mask:0xf bound_ctrl:1
	v_pk_fma_f32 v[16:17], v[88:89], v[148:149], v[136:137] op_sel_hi:[1,0,1]
	v_pk_fma_f32 v[18:19], v[90:91], v[148:149], v[138:139] op_sel_hi:[1,0,1]
	v_add_f32_dpp v216, v216, v216 row_ror:8 row_mask:0xf bank_mask:0xf bound_ctrl:1
	v_pk_fma_f32 v[140:141], v[16:17], v[92:93], v[140:141]
	v_pk_mul_f32 v[144:145], v[16:17], v[76:77]
	v_add_f32_dpp v216, v216, v216 row_ror:4 row_mask:0xf bank_mask:0xf bound_ctrl:1
	v_pk_fma_f32 v[142:143], v[18:19], v[94:95], v[142:143]
	v_pk_fma_f32 v[144:145], v[18:19], v[78:79], v[144:145]
	v_cndmask_b32_e64 v28, v28, v216, s[34:35]
	v_pk_fma_f32 v[16:17], v[108:109], v[148:149], v[140:141] op_sel:[0,1,0] op_sel_hi:[1,1,1]
	v_pk_fma_f32 v[18:19], v[110:111], v[148:149], v[142:143] op_sel:[0,1,0] op_sel_hi:[1,1,1]
	v_pk_mul_f32 v[146:147], v[16:17], v[96:97]
	v_pk_fma_f32 v[146:147], v[18:19], v[98:99], v[146:147]
	s_waitcnt lgkmcnt(6)
	v_pk_mul_f32 v[132:133], v[16:17], v[172:173]
	v_pk_mul_f32 v[134:135], v[16:17], v[192:193]
	v_add_f32_e32 v204, v144, v145
	v_pk_fma_f32 v[132:133], v[18:19], v[174:175], v[132:133]
	v_pk_fma_f32 v[134:135], v[18:19], v[194:195], v[134:135]
	v_add_f32_e32 v205, v146, v147
	v_pk_mul_f32 v[136:137], v[116:117], v[168:169] op_sel_hi:[0,1]
	v_add_f32_e32 v148, v132, v133
	v_add_f32_e32 v149, v134, v135
	v_pk_mul_f32 v[138:139], v[116:117], v[170:171] op_sel_hi:[0,1]
	v_add_f32_dpp v148, v148, v148 quad_perm:[1,0,3,2] row_mask:0xf bank_mask:0xf bound_ctrl:1
	v_add_f32_dpp v149, v149, v149 quad_perm:[1,0,3,2] row_mask:0xf bank_mask:0xf bound_ctrl:1
	v_pk_fma_f32 v[136:137], v[16:17], v[160:161], v[136:137]
	v_add_f32_dpp v148, v148, v148 quad_perm:[2,3,0,1] row_mask:0xf bank_mask:0xf bound_ctrl:1
	v_add_f32_dpp v149, v149, v149 quad_perm:[2,3,0,1] row_mask:0xf bank_mask:0xf bound_ctrl:1
	v_pk_fma_f32 v[138:139], v[18:19], v[162:163], v[138:139]
	v_add_f32_dpp v148, v148, v148 row_half_mirror row_mask:0xf bank_mask:0xf bound_ctrl:1
	v_add_f32_dpp v149, v149, v149 row_half_mirror row_mask:0xf bank_mask:0xf bound_ctrl:1
	ds_read_b128 v[44:47], v29 offset:30768
	ds_read_b128 v[64:67], v29 offset:32048
	ds_read_b128 v[40:43], v29 offset:30752
	ds_read2_b32 v[112:113], v123 offset0:0 offset1:20
	ds_read_b128 v[32:35], v29 offset:30720
	ds_read2_b32 v[118:119], v125 offset0:36 offset1:76
	ds_read_b128 v[48:51], v29 offset:30784
	ds_read_b128 v[60:63], v29 offset:32032
	ds_read_b128 v[52:55], v29 offset:32000
	ds_read_b128 v[36:39], v29 offset:30736
	ds_read_b128 v[68:71], v29 offset:32064
	ds_read_b128 v[56:59], v29 offset:32016
	s_waitcnt lgkmcnt(12)
	v_pk_mul_f32 v[140:141], v[116:117], v[188:189] op_sel:[1,0] op_sel_hi:[1,1]
	v_add_f32_dpp v148, v148, v148 row_mirror row_mask:0xf bank_mask:0xf bound_ctrl:1
	v_add_f32_dpp v149, v149, v149 row_mirror row_mask:0xf bank_mask:0xf bound_ctrl:1
	v_pk_mul_f32 v[142:143], v[116:117], v[190:191] op_sel:[1,0] op_sel_hi:[1,1]
	v_fmac_f32_e32 v149, v116, v121
	v_pk_fma_f32 v[16:17], v[176:177], v[148:149], v[136:137] op_sel_hi:[1,0,1]
	v_pk_fma_f32 v[18:19], v[178:179], v[148:149], v[138:139] op_sel_hi:[1,0,1]
	v_pk_fma_f32 v[140:141], v[16:17], v[180:181], v[140:141]
	v_pk_mul_f32 v[144:145], v[16:17], v[164:165]
	v_pk_fma_f32 v[142:143], v[18:19], v[182:183], v[142:143]
	v_pk_fma_f32 v[144:145], v[18:19], v[166:167], v[144:145]
	v_pk_fma_f32 v[16:17], v[196:197], v[148:149], v[140:141] op_sel:[0,1,0] op_sel_hi:[1,1,1]
	v_pk_fma_f32 v[18:19], v[198:199], v[148:149], v[142:143] op_sel:[0,1,0] op_sel_hi:[1,1,1]
	v_pk_mul_f32 v[146:147], v[16:17], v[184:185]
	v_pk_fma_f32 v[146:147], v[18:19], v[186:187], v[146:147]
	s_waitcnt lgkmcnt(7)
	v_pk_mul_f32 v[132:133], v[16:17], v[44:45]
	v_pk_mul_f32 v[134:135], v[16:17], v[64:65]
	v_add_f32_e32 v206, v144, v145
	v_pk_fma_f32 v[132:133], v[18:19], v[46:47], v[132:133]
	v_pk_fma_f32 v[134:135], v[18:19], v[66:67], v[134:135]
	v_add_f32_e32 v207, v146, v147
	v_pk_mul_f32 v[136:137], v[112:113], v[40:41] op_sel_hi:[0,1]
	v_add_f32_e32 v148, v132, v133
	v_cndmask_b32_e64 v208, v204, v205, s[10:11]
	v_add_f32_e32 v149, v134, v135
	v_pk_mul_f32 v[138:139], v[112:113], v[42:43] op_sel_hi:[0,1]
	v_cndmask_b32_e64 v209, v205, v204, s[10:11]
	v_add_f32_dpp v148, v148, v148 quad_perm:[1,0,3,2] row_mask:0xf bank_mask:0xf bound_ctrl:1
	v_add_f32_dpp v149, v149, v149 quad_perm:[1,0,3,2] row_mask:0xf bank_mask:0xf bound_ctrl:1
	v_cndmask_b32_e64 v210, v206, v207, s[10:11]
	v_pk_fma_f32 v[136:137], v[16:17], v[32:33], v[136:137]
	v_add_f32_dpp v148, v148, v148 quad_perm:[2,3,0,1] row_mask:0xf bank_mask:0xf bound_ctrl:1
	v_cndmask_b32_e64 v211, v207, v206, s[10:11]
	v_add_f32_dpp v149, v149, v149 quad_perm:[2,3,0,1] row_mask:0xf bank_mask:0xf bound_ctrl:1
	v_pk_fma_f32 v[138:139], v[18:19], v[34:35], v[138:139]
	v_add_f32_dpp v212, v209, v208 quad_perm:[1,0,3,2] row_mask:0xf bank_mask:0xf bound_ctrl:1
	v_add_f32_dpp v148, v148, v148 row_half_mirror row_mask:0xf bank_mask:0xf bound_ctrl:1
	v_add_f32_dpp v149, v149, v149 row_half_mirror row_mask:0xf bank_mask:0xf bound_ctrl:1
	v_add_f32_dpp v213, v211, v210 quad_perm:[1,0,3,2] row_mask:0xf bank_mask:0xf bound_ctrl:1
	ds_read_b128 v[84:87], v29 offset:33328
	ds_read_b128 v[104:107], v29 offset:34608
	ds_read_b128 v[80:83], v29 offset:33312
	ds_read2_b32 v[114:115], v123 offset0:40 offset1:60
	ds_read_b128 v[72:75], v29 offset:33280
	ds_read_b128 v[88:91], v29 offset:33344
	ds_read_b128 v[100:103], v29 offset:34592
	ds_read_b128 v[92:95], v29 offset:34560
	ds_read_b128 v[76:79], v29 offset:33296
	ds_read_b128 v[108:111], v29 offset:34624
	ds_read_b128 v[96:99], v29 offset:34576
	s_waitcnt lgkmcnt(11)
	v_pk_mul_f32 v[140:141], v[112:113], v[60:61] op_sel:[1,0] op_sel_hi:[1,1]
	v_cndmask_b32_e64 v214, v212, v213, s[14:15]
	v_add_f32_dpp v148, v148, v148 row_mirror row_mask:0xf bank_mask:0xf bound_ctrl:1
	v_add_f32_dpp v149, v149, v149 row_mirror row_mask:0xf bank_mask:0xf bound_ctrl:1
	v_cndmask_b32_e64 v215, v213, v212, s[14:15]
	v_pk_mul_f32 v[142:143], v[112:113], v[62:63] op_sel:[1,0] op_sel_hi:[1,1]
	v_fmac_f32_e32 v149, v112, v118
	v_add_f32_dpp v216, v215, v214 quad_perm:[2,3,0,1] row_mask:0xf bank_mask:0xf bound_ctrl:1
	v_pk_fma_f32 v[16:17], v[48:49], v[148:149], v[136:137] op_sel_hi:[1,0,1]
	v_pk_fma_f32 v[18:19], v[50:51], v[148:149], v[138:139] op_sel_hi:[1,0,1]
	v_add_f32_dpp v216, v216, v216 row_ror:8 row_mask:0xf bank_mask:0xf bound_ctrl:1
	v_pk_fma_f32 v[140:141], v[16:17], v[52:53], v[140:141]
	v_pk_mul_f32 v[144:145], v[16:17], v[36:37]
	v_add_f32_dpp v216, v216, v216 row_ror:4 row_mask:0xf bank_mask:0xf bound_ctrl:1
	v_pk_fma_f32 v[142:143], v[18:19], v[54:55], v[142:143]
	v_pk_fma_f32 v[144:145], v[18:19], v[38:39], v[144:145]
	v_cndmask_b32_e64 v28, v28, v216, s[36:37]
	v_pk_fma_f32 v[16:17], v[68:69], v[148:149], v[140:141] op_sel:[0,1,0] op_sel_hi:[1,1,1]
	v_pk_fma_f32 v[18:19], v[70:71], v[148:149], v[142:143] op_sel:[0,1,0] op_sel_hi:[1,1,1]
	v_pk_mul_f32 v[146:147], v[16:17], v[56:57]
	v_pk_fma_f32 v[146:147], v[18:19], v[58:59], v[146:147]
	s_waitcnt lgkmcnt(6)
	v_pk_mul_f32 v[132:133], v[16:17], v[84:85]
	v_pk_mul_f32 v[134:135], v[16:17], v[104:105]
	v_add_f32_e32 v200, v144, v145
	v_pk_fma_f32 v[132:133], v[18:19], v[86:87], v[132:133]
	v_pk_fma_f32 v[134:135], v[18:19], v[106:107], v[134:135]
	v_add_f32_e32 v201, v146, v147
	v_pk_mul_f32 v[136:137], v[114:115], v[80:81] op_sel_hi:[0,1]
	v_add_f32_e32 v148, v132, v133
	v_add_f32_e32 v149, v134, v135
	v_pk_mul_f32 v[138:139], v[114:115], v[82:83] op_sel_hi:[0,1]
	v_add_f32_dpp v148, v148, v148 quad_perm:[1,0,3,2] row_mask:0xf bank_mask:0xf bound_ctrl:1
	v_add_f32_dpp v149, v149, v149 quad_perm:[1,0,3,2] row_mask:0xf bank_mask:0xf bound_ctrl:1
	v_pk_fma_f32 v[136:137], v[16:17], v[72:73], v[136:137]
	v_add_f32_dpp v148, v148, v148 quad_perm:[2,3,0,1] row_mask:0xf bank_mask:0xf bound_ctrl:1
	v_add_f32_dpp v149, v149, v149 quad_perm:[2,3,0,1] row_mask:0xf bank_mask:0xf bound_ctrl:1
	v_pk_fma_f32 v[138:139], v[18:19], v[74:75], v[138:139]
	v_add_f32_dpp v148, v148, v148 row_half_mirror row_mask:0xf bank_mask:0xf bound_ctrl:1
	v_add_f32_dpp v149, v149, v149 row_half_mirror row_mask:0xf bank_mask:0xf bound_ctrl:1
	ds_read_b128 v[172:175], v29 offset:35888
	ds_read_b128 v[192:195], v29 offset:37168
	ds_read_b128 v[168:171], v29 offset:35872
	ds_read2_b32 v[116:117], v123 offset0:80 offset1:100
	ds_read_b128 v[160:163], v29 offset:35840
	ds_read2_b32 v[120:121], v125 offset0:116 offset1:156
	ds_read_b128 v[176:179], v29 offset:35904
	ds_read_b128 v[188:191], v29 offset:37152
	ds_read_b128 v[180:183], v29 offset:37120
	ds_read_b128 v[164:167], v29 offset:35856
	ds_read_b128 v[196:199], v29 offset:37184
	ds_read_b128 v[184:187], v29 offset:37136
	s_waitcnt lgkmcnt(12)
	v_pk_mul_f32 v[140:141], v[114:115], v[100:101] op_sel:[1,0] op_sel_hi:[1,1]
	v_add_f32_dpp v148, v148, v148 row_mirror row_mask:0xf bank_mask:0xf bound_ctrl:1
	v_add_f32_dpp v149, v149, v149 row_mirror row_mask:0xf bank_mask:0xf bound_ctrl:1
	v_pk_mul_f32 v[142:143], v[114:115], v[102:103] op_sel:[1,0] op_sel_hi:[1,1]
	v_fmac_f32_e32 v149, v114, v119
	v_pk_fma_f32 v[16:17], v[88:89], v[148:149], v[136:137] op_sel_hi:[1,0,1]
	v_pk_fma_f32 v[18:19], v[90:91], v[148:149], v[138:139] op_sel_hi:[1,0,1]
	v_pk_fma_f32 v[140:141], v[16:17], v[92:93], v[140:141]
	v_pk_mul_f32 v[144:145], v[16:17], v[76:77]
	v_pk_fma_f32 v[142:143], v[18:19], v[94:95], v[142:143]
	v_pk_fma_f32 v[144:145], v[18:19], v[78:79], v[144:145]
	v_pk_fma_f32 v[16:17], v[108:109], v[148:149], v[140:141] op_sel:[0,1,0] op_sel_hi:[1,1,1]
	v_pk_fma_f32 v[18:19], v[110:111], v[148:149], v[142:143] op_sel:[0,1,0] op_sel_hi:[1,1,1]
	v_pk_mul_f32 v[146:147], v[16:17], v[96:97]
	v_pk_fma_f32 v[146:147], v[18:19], v[98:99], v[146:147]
	s_waitcnt lgkmcnt(7)
	v_pk_mul_f32 v[132:133], v[16:17], v[172:173]
	v_pk_mul_f32 v[134:135], v[16:17], v[192:193]
	v_add_f32_e32 v202, v144, v145
	v_pk_fma_f32 v[132:133], v[18:19], v[174:175], v[132:133]
	v_pk_fma_f32 v[134:135], v[18:19], v[194:195], v[134:135]
	v_add_f32_e32 v203, v146, v147
	v_pk_mul_f32 v[136:137], v[116:117], v[168:169] op_sel_hi:[0,1]
	v_add_f32_e32 v148, v132, v133
	v_cndmask_b32_e64 v208, v200, v201, s[10:11]
	v_add_f32_e32 v149, v134, v135
	v_pk_mul_f32 v[138:139], v[116:117], v[170:171] op_sel_hi:[0,1]
	v_cndmask_b32_e64 v209, v201, v200, s[10:11]
	v_add_f32_dpp v148, v148, v148 quad_perm:[1,0,3,2] row_mask:0xf bank_mask:0xf bound_ctrl:1
	v_add_f32_dpp v149, v149, v149 quad_perm:[1,0,3,2] row_mask:0xf bank_mask:0xf bound_ctrl:1
	v_cndmask_b32_e64 v210, v202, v203, s[10:11]
	v_pk_fma_f32 v[136:137], v[16:17], v[160:161], v[136:137]
	v_add_f32_dpp v148, v148, v148 quad_perm:[2,3,0,1] row_mask:0xf bank_mask:0xf bound_ctrl:1
	v_cndmask_b32_e64 v211, v203, v202, s[10:11]
	v_add_f32_dpp v149, v149, v149 quad_perm:[2,3,0,1] row_mask:0xf bank_mask:0xf bound_ctrl:1
	v_pk_fma_f32 v[138:139], v[18:19], v[162:163], v[138:139]
	v_add_f32_dpp v212, v209, v208 quad_perm:[1,0,3,2] row_mask:0xf bank_mask:0xf bound_ctrl:1
	v_add_f32_dpp v148, v148, v148 row_half_mirror row_mask:0xf bank_mask:0xf bound_ctrl:1
	v_add_f32_dpp v149, v149, v149 row_half_mirror row_mask:0xf bank_mask:0xf bound_ctrl:1
	v_add_f32_dpp v213, v211, v210 quad_perm:[1,0,3,2] row_mask:0xf bank_mask:0xf bound_ctrl:1
	ds_read_b128 v[44:47], v29 offset:38448
	ds_read_b128 v[64:67], v29 offset:39728
	ds_read_b128 v[40:43], v29 offset:38432
	ds_read2_b32 v[112:113], v123 offset0:120 offset1:140
	ds_read_b128 v[32:35], v29 offset:38400
	ds_read_b128 v[48:51], v29 offset:38464
	ds_read_b128 v[60:63], v29 offset:39712
	ds_read_b128 v[52:55], v29 offset:39680
	ds_read_b128 v[36:39], v29 offset:38416
	ds_read_b128 v[68:71], v29 offset:39744
	ds_read_b128 v[56:59], v29 offset:39696
	s_waitcnt lgkmcnt(11)
	v_pk_mul_f32 v[140:141], v[116:117], v[188:189] op_sel:[1,0] op_sel_hi:[1,1]
	v_cndmask_b32_e64 v214, v212, v213, s[14:15]
	v_add_f32_dpp v148, v148, v148 row_mirror row_mask:0xf bank_mask:0xf bound_ctrl:1
	v_add_f32_dpp v149, v149, v149 row_mirror row_mask:0xf bank_mask:0xf bound_ctrl:1
	v_cndmask_b32_e64 v215, v213, v212, s[14:15]
	v_pk_mul_f32 v[142:143], v[116:117], v[190:191] op_sel:[1,0] op_sel_hi:[1,1]
	v_fmac_f32_e32 v149, v116, v120
	v_add_f32_dpp v216, v215, v214 quad_perm:[2,3,0,1] row_mask:0xf bank_mask:0xf bound_ctrl:1
	v_pk_fma_f32 v[16:17], v[176:177], v[148:149], v[136:137] op_sel_hi:[1,0,1]
	v_pk_fma_f32 v[18:19], v[178:179], v[148:149], v[138:139] op_sel_hi:[1,0,1]
	v_add_f32_dpp v216, v216, v216 row_ror:8 row_mask:0xf bank_mask:0xf bound_ctrl:1
	v_pk_fma_f32 v[140:141], v[16:17], v[180:181], v[140:141]
	v_pk_mul_f32 v[144:145], v[16:17], v[164:165]
	v_add_f32_dpp v216, v216, v216 row_ror:4 row_mask:0xf bank_mask:0xf bound_ctrl:1
	v_pk_fma_f32 v[142:143], v[18:19], v[182:183], v[142:143]
	v_pk_fma_f32 v[144:145], v[18:19], v[166:167], v[144:145]
	v_cndmask_b32_e64 v28, v28, v216, s[42:43]
	v_pk_fma_f32 v[16:17], v[196:197], v[148:149], v[140:141] op_sel:[0,1,0] op_sel_hi:[1,1,1]
	v_pk_fma_f32 v[18:19], v[198:199], v[148:149], v[142:143] op_sel:[0,1,0] op_sel_hi:[1,1,1]
	v_pk_mul_f32 v[146:147], v[16:17], v[184:185]
	v_pk_fma_f32 v[146:147], v[18:19], v[186:187], v[146:147]
	s_waitcnt lgkmcnt(6)
	v_pk_mul_f32 v[132:133], v[16:17], v[44:45]
	v_pk_mul_f32 v[134:135], v[16:17], v[64:65]
	v_add_f32_e32 v204, v144, v145
	v_pk_fma_f32 v[132:133], v[18:19], v[46:47], v[132:133]
	v_pk_fma_f32 v[134:135], v[18:19], v[66:67], v[134:135]
	v_add_f32_e32 v205, v146, v147
	v_pk_mul_f32 v[136:137], v[112:113], v[40:41] op_sel_hi:[0,1]
	v_add_f32_e32 v148, v132, v133
	v_add_f32_e32 v149, v134, v135
	v_pk_mul_f32 v[138:139], v[112:113], v[42:43] op_sel_hi:[0,1]
	v_add_f32_dpp v148, v148, v148 quad_perm:[1,0,3,2] row_mask:0xf bank_mask:0xf bound_ctrl:1
	v_add_f32_dpp v149, v149, v149 quad_perm:[1,0,3,2] row_mask:0xf bank_mask:0xf bound_ctrl:1
	v_pk_fma_f32 v[136:137], v[16:17], v[32:33], v[136:137]
	v_add_f32_dpp v148, v148, v148 quad_perm:[2,3,0,1] row_mask:0xf bank_mask:0xf bound_ctrl:1
	v_add_f32_dpp v149, v149, v149 quad_perm:[2,3,0,1] row_mask:0xf bank_mask:0xf bound_ctrl:1
	v_pk_fma_f32 v[138:139], v[18:19], v[34:35], v[138:139]
	v_add_f32_dpp v148, v148, v148 row_half_mirror row_mask:0xf bank_mask:0xf bound_ctrl:1
	v_add_f32_dpp v149, v149, v149 row_half_mirror row_mask:0xf bank_mask:0xf bound_ctrl:1
	s_waitcnt lgkmcnt(0)
	v_pk_mul_f32 v[140:141], v[112:113], v[60:61] op_sel:[1,0] op_sel_hi:[1,1]
	v_add_f32_dpp v148, v148, v148 row_mirror row_mask:0xf bank_mask:0xf bound_ctrl:1
	v_add_f32_dpp v149, v149, v149 row_mirror row_mask:0xf bank_mask:0xf bound_ctrl:1
	v_pk_mul_f32 v[142:143], v[112:113], v[62:63] op_sel:[1,0] op_sel_hi:[1,1]
	v_fmac_f32_e32 v149, v112, v121
	v_pk_fma_f32 v[16:17], v[48:49], v[148:149], v[136:137] op_sel_hi:[1,0,1]
	v_pk_fma_f32 v[18:19], v[50:51], v[148:149], v[138:139] op_sel_hi:[1,0,1]
	v_pk_fma_f32 v[140:141], v[16:17], v[52:53], v[140:141]
	v_pk_mul_f32 v[144:145], v[16:17], v[36:37]
	v_pk_fma_f32 v[142:143], v[18:19], v[54:55], v[142:143]
	v_pk_fma_f32 v[144:145], v[18:19], v[38:39], v[144:145]
	v_pk_fma_f32 v[16:17], v[68:69], v[148:149], v[140:141] op_sel:[0,1,0] op_sel_hi:[1,1,1]
	v_pk_fma_f32 v[18:19], v[70:71], v[148:149], v[142:143] op_sel:[0,1,0] op_sel_hi:[1,1,1]
	v_pk_mul_f32 v[146:147], v[16:17], v[56:57]
	v_pk_fma_f32 v[146:147], v[18:19], v[58:59], v[146:147]
	v_add_f32_e32 v206, v144, v145
	v_add_f32_e32 v207, v146, v147
	v_cndmask_b32_e64 v208, v204, v205, s[10:11]
	v_cndmask_b32_e64 v209, v205, v204, s[10:11]
	v_cndmask_b32_e64 v210, v206, v207, s[10:11]
	v_cndmask_b32_e64 v211, v207, v206, s[10:11]
	v_add_f32_dpp v212, v209, v208 quad_perm:[1,0,3,2] row_mask:0xf bank_mask:0xf bound_ctrl:1
	s_nop 0
	v_add_f32_dpp v213, v211, v210 quad_perm:[1,0,3,2] row_mask:0xf bank_mask:0xf bound_ctrl:1
	v_cndmask_b32_e64 v214, v212, v213, s[14:15]
	v_cndmask_b32_e64 v215, v213, v212, s[14:15]
	s_nop 1
	v_add_f32_dpp v216, v215, v214 quad_perm:[2,3,0,1] row_mask:0xf bank_mask:0xf bound_ctrl:1
	s_nop 1
	v_add_f32_dpp v216, v216, v216 row_ror:8 row_mask:0xf bank_mask:0xf bound_ctrl:1
	s_nop 1
	v_add_f32_dpp v216, v216, v216 row_ror:4 row_mask:0xf bank_mask:0xf bound_ctrl:1
	v_cndmask_b32_e64 v28, v28, v216, s[44:45]
	v_add_co_u32_e32 v218, vcc, 0x4d04000, v12
	s_nop 1
	v_addc_co_u32_e32 v219, vcc, 0, v13, vcc
	global_store_dword v[218:219], v28, off
